# sel_ip: hand-written unmasked selected-pair body with in-place accumulators (no hand-over moves after unmasked iterations), scalar softmax
# speedup vs baseline: 1.0124x; 1.0005x over previous
.LBB0_1044:
	s_lshl_b32 s29, s22, 6
	v_subrev_u32_e32 v1, s29, v139
	s_add_i32 s29, s81, 0xffffff80
	s_and_b32 s29, s29, 0x80
	s_mulk_i32 s29, 0xa0
	v_add_u32_e32 v143, s29, v153
	ds_read_b128 v[88:91], v143
	ds_read_b128 v[92:95], v143 offset:64
	ds_read_b128 v[96:99], v143 offset:2560
	ds_read_b128 v[100:103], v143 offset:2624
	ds_read_b128 v[104:107], v143 offset:5120
	ds_read_b128 v[108:111], v143 offset:5184
	ds_read_b128 v[112:115], v143 offset:7680
	ds_read_b128 v[116:119], v143 offset:7744
	s_lshl_b32 s29, s23, 6
	v_subrev_u32_e32 v0, s29, v139
	s_max_i32 s22, s22, s23
	s_cmp_ge_i32 s22, s76
	s_setprio 1
	v_cvt_f32_i32_e32 v147, v1
	v_cvt_f32_i32_e32 v141, v0
	s_mov_b64 s[22:23], -1
	s_cbranch_scc0 .LBB0_1046
	s_mov_b32 s101, 1
	s_waitcnt lgkmcnt(7)
	v_mfma_f32_16x16x32_bf16 v[2:5], v[88:91], v[60:63], 0
	s_waitcnt lgkmcnt(5)
	v_mfma_f32_16x16x32_bf16 v[6:9], v[96:99], v[60:63], 0
	s_waitcnt lgkmcnt(3)
	v_mfma_f32_16x16x32_bf16 v[10:13], v[104:107], v[60:63], 0
	s_waitcnt lgkmcnt(1)
	v_mfma_f32_16x16x32_bf16 v[80:83], v[112:115], v[60:63], 0
	v_mfma_f32_16x16x32_bf16 v[2:5], v[92:95], v[56:59], v[2:5]
	v_mfma_f32_16x16x32_bf16 v[6:9], v[100:103], v[56:59], v[6:9]
	v_mfma_f32_16x16x32_bf16 v[10:13], v[108:111], v[56:59], v[10:13]
	s_waitcnt lgkmcnt(0)
	v_mfma_f32_16x16x32_bf16 v[80:83], v[116:119], v[56:59], v[80:83]
	s_setprio 0
	v_fma_f32 v14, -v146, v147, v192
	s_nop 1
	v_fmamk_f32 v2, v2, 0x3e38aa3b, v14
	v_cmp_gt_u32_e32 vcc, s70, v1
	v_add_f32_e32 v15, v146, v14
	s_and_b64 vcc, vcc, s[20:21]
	v_fmac_f32_e32 v15, 0x3e38aa3b, v3
	v_add_f32_e32 v3, v137, v14
	v_cndmask_b32_e32 v2, v179, v2, vcc
	v_cmp_lt_i32_e32 vcc, 0, v1
	v_fmac_f32_e32 v3, 0x3e38aa3b, v4
	v_add_f32_e32 v4, v188, v14
	s_and_b64 vcc, vcc, s[20:21]
	v_add_u32_e32 v14, -2, v1
	v_fmac_f32_e32 v4, 0x3e38aa3b, v5
	s_nop 0
	v_cndmask_b32_e32 v5, v179, v15, vcc
	v_cmp_gt_u32_e32 vcc, s70, v14
	s_and_b64 vcc, s[20:21], vcc
	v_add_u32_e32 v14, -3, v1
	v_cndmask_b32_e32 v3, v179, v3, vcc
	v_cmp_gt_u32_e32 vcc, s70, v14
	v_exp_f32_e32 v14, v2
	v_fma_f32 v2, -v146, v147, v189
	s_and_b64 vcc, s[20:21], vcc
	v_exp_f32_e32 v193, v3
	v_fmamk_f32 v3, v6, 0x3e38aa3b, v2
	v_add_u32_e32 v6, -16, v1
	v_cndmask_b32_e32 v4, v179, v4, vcc
	v_cmp_gt_u32_e32 vcc, s70, v6
	v_exp_f32_e32 v195, v4
	v_add_f32_e32 v4, v146, v2
	s_and_b64 vcc, s[20:21], vcc
	v_subrev_u32_e32 v6, 17, v1
	v_fmac_f32_e32 v4, 0x3e38aa3b, v7
	v_cndmask_b32_e32 v3, v179, v3, vcc
	v_cmp_gt_u32_e32 vcc, s70, v6
	v_exp_f32_e32 v15, v5
	v_add_f32_e32 v5, v137, v2
	s_and_b64 vcc, vcc, s[20:21]
	v_subrev_u32_e32 v6, 18, v1
	v_fmac_f32_e32 v5, 0x3e38aa3b, v8
	v_cndmask_b32_e32 v4, v179, v4, vcc
	v_cmp_gt_u32_e32 vcc, s70, v6
	v_add_f32_e32 v2, v188, v2
	s_and_b64 vcc, s[20:21], vcc
	v_subrev_u32_e32 v6, 19, v1
	v_fmac_f32_e32 v2, 0x3e38aa3b, v9
	v_cndmask_b32_e32 v5, v179, v5, vcc
	v_cmp_gt_u32_e32 vcc, s70, v6
	s_and_b64 vcc, s[20:21], vcc
	v_subrev_u32_e32 v6, 32, v1
	v_cndmask_b32_e32 v2, v179, v2, vcc
	v_exp_f32_e32 v199, v2
	v_fma_f32 v2, -v146, v147, v190
	v_exp_f32_e32 v196, v3
	v_fmamk_f32 v3, v10, 0x3e38aa3b, v2
	v_cmp_gt_u32_e32 vcc, s70, v6
	v_exp_f32_e32 v197, v4
	v_add_f32_e32 v4, v146, v2
	s_and_b64 vcc, s[20:21], vcc
	v_subrev_u32_e32 v6, 33, v1
	v_fmac_f32_e32 v4, 0x3e38aa3b, v11
	v_cndmask_b32_e32 v3, v179, v3, vcc
	v_cmp_gt_u32_e32 vcc, s70, v6
	v_exp_f32_e32 v198, v5
	v_add_f32_e32 v5, v137, v2
	s_and_b64 vcc, vcc, s[20:21]
	v_subrev_u32_e32 v6, 34, v1
	v_fmac_f32_e32 v5, 0x3e38aa3b, v12
	v_cndmask_b32_e32 v4, v179, v4, vcc
	v_cmp_gt_u32_e32 vcc, s70, v6
	v_add_f32_e32 v2, v188, v2
	s_and_b64 vcc, s[20:21], vcc
	v_subrev_u32_e32 v6, 35, v1
	v_fmac_f32_e32 v2, 0x3e38aa3b, v13
	v_cndmask_b32_e32 v5, v179, v5, vcc
	v_cmp_gt_u32_e32 vcc, s70, v6
	s_and_b64 vcc, s[20:21], vcc
	v_subrev_u32_e32 v6, 48, v1
	v_cndmask_b32_e32 v2, v179, v2, vcc
	v_exp_f32_e32 v221, v2
	v_fma_f32 v2, -v146, v147, v191
	v_exp_f32_e32 v218, v3
	v_fmamk_f32 v3, v80, 0x3e38aa3b, v2
	v_cmp_gt_u32_e32 vcc, s70, v6
	v_exp_f32_e32 v219, v4
	v_add_f32_e32 v4, v146, v2
	s_and_b64 vcc, s[20:21], vcc
	v_subrev_u32_e32 v6, 49, v1
	v_fmac_f32_e32 v4, 0x3e38aa3b, v81
	v_cndmask_b32_e32 v3, v179, v3, vcc
	v_cmp_gt_u32_e32 vcc, s70, v6
	v_exp_f32_e32 v220, v5
	v_add_f32_e32 v5, v137, v2
	s_and_b64 vcc, vcc, s[20:21]
	v_subrev_u32_e32 v6, 50, v1
	v_fmac_f32_e32 v5, 0x3e38aa3b, v82
	v_cndmask_b32_e32 v4, v179, v4, vcc
	v_cmp_gt_u32_e32 vcc, s70, v6
	v_add_f32_e32 v2, v188, v2
	s_and_b64 vcc, s[20:21], vcc
	v_subrev_u32_e32 v1, 51, v1
	v_fmac_f32_e32 v2, 0x3e38aa3b, v83
	v_cndmask_b32_e32 v5, v179, v5, vcc
	v_cmp_gt_u32_e32 vcc, s70, v1
	s_and_b64 vcc, s[20:21], vcc
	v_exp_f32_e32 v222, v3
	v_cndmask_b32_e32 v1, v179, v2, vcc
	v_exp_f32_e32 v223, v4
	v_exp_f32_e32 v224, v5
	ds_read_b128 v[2:5], v143 offset:40960
	ds_read_b128 v[6:9], v143 offset:43520
	ds_read_b128 v[10:13], v143 offset:46080
	ds_read_b128 v[80:83], v143 offset:48640
	v_exp_f32_e32 v1, v1
	s_nop 0
	v_cvt_pk_bf16_f32 v194, v14, v15
	v_cvt_pk_bf16_f32 v195, v193, v195
	v_cvt_pk_bf16_f32 v196, v196, v197
	v_cvt_pk_bf16_f32 v197, v198, v199
	s_setprio 1
	s_mov_b32 s30, s28
	s_mov_b32 s31, s28
	s_waitcnt lgkmcnt(0)
	v_mfma_f32_16x16x32_bf16 v[198:201], v[80:83], v[194:197], v[84:87]
	s_mov_b32 s29, s28
	v_mov_b64_e32 v[82:83], s[30:31]
	v_mov_b64_e32 v[80:81], s[28:29]
	v_mfma_f32_16x16x32_bf16 v[2:5], v[2:5], v[194:197], v[36:39]
	v_mfma_f32_16x16x32_bf16 v[6:9], v[6:9], v[194:197], v[40:43]
	v_mfma_f32_16x16x32_bf16 v[10:13], v[10:13], v[194:197], v[44:47]
	v_mfma_f32_16x16x32_bf16 v[194:197], v[80:83], v[194:197], v[32:35]
	s_setprio 0
	ds_read_b128 v[202:205], v143 offset:41024
	ds_read_b128 v[206:209], v143 offset:43584
	ds_read_b128 v[210:213], v143 offset:46144
	ds_read_b128 v[214:217], v143 offset:48704
	v_cvt_pk_bf16_f32 v218, v218, v219
	v_cvt_pk_bf16_f32 v219, v220, v221
	v_cvt_pk_bf16_f32 v220, v222, v223
	v_cvt_pk_bf16_f32 v221, v224, v1
	s_setprio 1
	s_waitcnt lgkmcnt(3)
	v_mfma_f32_16x16x32_bf16 v[2:5], v[202:205], v[218:221], v[2:5]
	s_waitcnt lgkmcnt(2)
	v_mfma_f32_16x16x32_bf16 v[6:9], v[206:209], v[218:221], v[6:9]
	s_waitcnt lgkmcnt(1)
	v_mfma_f32_16x16x32_bf16 v[10:13], v[210:213], v[218:221], v[10:13]
	s_waitcnt lgkmcnt(0)
	v_mfma_f32_16x16x32_bf16 v[198:201], v[214:217], v[218:221], v[198:201]
	v_mfma_f32_16x16x32_bf16 v[194:197], v[80:83], v[218:221], v[194:197]
	s_setprio 0
	s_sub_i32 s22, s81, 64
	s_and_b32 s22, s22, 0xc0
	s_mulk_i32 s22, 0xa0
	v_add_u32_e32 v193, s22, v153
	ds_read_b128 v[202:205], v193
	ds_read_b128 v[206:209], v193 offset:64
	ds_read_b128 v[210:213], v193 offset:2560
	ds_read_b128 v[214:217], v193 offset:2624
	ds_read_b128 v[218:221], v193 offset:5120
	ds_read_b128 v[222:225], v193 offset:5184
	ds_read_b128 v[226:229], v193 offset:7680
	ds_read_b128 v[230:233], v193 offset:7744
	s_setprio 1
	s_waitcnt lgkmcnt(7)
	v_mfma_f32_16x16x32_bf16 v[202:205], v[202:205], v[60:63], 0
	s_waitcnt lgkmcnt(6)
	v_mfma_f32_16x16x32_bf16 v[202:205], v[206:209], v[56:59], v[202:205]
	s_waitcnt lgkmcnt(5)
	v_mfma_f32_16x16x32_bf16 v[206:209], v[210:213], v[60:63], 0
	s_waitcnt lgkmcnt(4)
	v_mfma_f32_16x16x32_bf16 v[206:209], v[214:217], v[56:59], v[206:209]
	s_waitcnt lgkmcnt(3)
	v_mfma_f32_16x16x32_bf16 v[210:213], v[218:221], v[60:63], 0
	s_waitcnt lgkmcnt(1)
	v_mfma_f32_16x16x32_bf16 v[214:217], v[226:229], v[60:63], 0
	v_mfma_f32_16x16x32_bf16 v[210:213], v[222:225], v[56:59], v[210:213]
	s_waitcnt lgkmcnt(0)
	v_mfma_f32_16x16x32_bf16 v[214:217], v[230:233], v[56:59], v[214:217]
	s_setprio 0
	v_fma_f32 v1, -v146, v141, v192
	v_fmamk_f32 v14, v202, 0x3e38aa3b, v1
	v_cmp_gt_u32_e32 vcc, s70, v0
	v_add_f32_e32 v15, v146, v1
	s_and_b64 vcc, vcc, s[0:1]
	v_fmac_f32_e32 v15, 0x3e38aa3b, v203
	v_cndmask_b32_e32 v14, v179, v14, vcc
	v_cmp_lt_i32_e32 vcc, 0, v0
	v_add_f32_e32 v202, v137, v1
	s_and_b64 vcc, vcc, s[0:1]
	v_add_u32_e32 v203, -2, v0
	v_fmac_f32_e32 v202, 0x3e38aa3b, v204
	v_cndmask_b32_e32 v15, v179, v15, vcc
	v_cmp_gt_u32_e32 vcc, s70, v203
	s_and_b64 vcc, s[0:1], vcc
	v_add_f32_e32 v1, v188, v1
	v_cndmask_b32_e32 v202, v179, v202, vcc
	v_add_u32_e32 v203, -3, v0
	v_fmac_f32_e32 v1, 0x3e38aa3b, v205
	v_cmp_gt_u32_e32 vcc, s70, v203
	v_exp_f32_e32 v219, v202
	v_fma_f32 v202, -v146, v141, v189
	s_and_b64 vcc, s[0:1], vcc
	v_fmamk_f32 v203, v206, 0x3e38aa3b, v202
	v_add_u32_e32 v206, -16, v0
	v_cndmask_b32_e32 v1, v179, v1, vcc
	v_cmp_gt_u32_e32 vcc, s70, v206
	v_add_f32_e32 v204, v146, v202
	s_and_b64 vcc, s[0:1], vcc
	v_subrev_u32_e32 v206, 17, v0
	v_fmac_f32_e32 v204, 0x3e38aa3b, v207
	v_cndmask_b32_e32 v203, v179, v203, vcc
	v_cmp_gt_u32_e32 vcc, s70, v206
	v_add_f32_e32 v205, v137, v202
	s_and_b64 vcc, vcc, s[0:1]
	v_subrev_u32_e32 v206, 18, v0
	v_fmac_f32_e32 v205, 0x3e38aa3b, v208
	v_cndmask_b32_e32 v204, v179, v204, vcc
	v_cmp_gt_u32_e32 vcc, s70, v206
	v_add_f32_e32 v202, v188, v202
	s_and_b64 vcc, s[0:1], vcc
	v_subrev_u32_e32 v206, 19, v0
	v_fmac_f32_e32 v202, 0x3e38aa3b, v209
	v_cndmask_b32_e32 v205, v179, v205, vcc
	v_cmp_gt_u32_e32 vcc, s70, v206
	s_and_b64 vcc, s[0:1], vcc
	v_subrev_u32_e32 v206, 32, v0
	v_cndmask_b32_e32 v202, v179, v202, vcc
	v_exp_f32_e32 v223, v202
	v_fma_f32 v202, -v146, v141, v190
	v_exp_f32_e32 v220, v203
	v_fmamk_f32 v203, v210, 0x3e38aa3b, v202
	v_cmp_gt_u32_e32 vcc, s70, v206
	v_exp_f32_e32 v221, v204
	v_add_f32_e32 v204, v146, v202
	s_and_b64 vcc, s[0:1], vcc
	v_subrev_u32_e32 v206, 33, v0
	v_fmac_f32_e32 v204, 0x3e38aa3b, v211
	v_cndmask_b32_e32 v203, v179, v203, vcc
	v_cmp_gt_u32_e32 vcc, s70, v206
	v_exp_f32_e32 v222, v205
	v_add_f32_e32 v205, v137, v202
	s_and_b64 vcc, vcc, s[0:1]
	v_subrev_u32_e32 v206, 34, v0
	v_fmac_f32_e32 v205, 0x3e38aa3b, v212
	v_cndmask_b32_e32 v204, v179, v204, vcc
	v_cmp_gt_u32_e32 vcc, s70, v206
	v_add_f32_e32 v202, v188, v202
	s_and_b64 vcc, s[0:1], vcc
	v_subrev_u32_e32 v206, 35, v0
	v_fmac_f32_e32 v202, 0x3e38aa3b, v213
	v_cndmask_b32_e32 v205, v179, v205, vcc
	v_cmp_gt_u32_e32 vcc, s70, v206
	s_and_b64 vcc, s[0:1], vcc
	v_subrev_u32_e32 v206, 48, v0
	v_cndmask_b32_e32 v202, v179, v202, vcc
	v_exp_f32_e32 v227, v202
	v_fma_f32 v202, -v146, v141, v191
	v_exp_f32_e32 v224, v203
	v_fmamk_f32 v203, v214, 0x3e38aa3b, v202
	v_cmp_gt_u32_e32 vcc, s70, v206
	v_exp_f32_e32 v225, v204
	v_add_f32_e32 v204, v146, v202
	s_and_b64 vcc, s[0:1], vcc
	v_subrev_u32_e32 v206, 49, v0
	v_fmac_f32_e32 v204, 0x3e38aa3b, v215
	v_cndmask_b32_e32 v203, v179, v203, vcc
	v_cmp_gt_u32_e32 vcc, s70, v206
	v_exp_f32_e32 v226, v205
	v_add_f32_e32 v205, v137, v202
	s_and_b64 vcc, vcc, s[0:1]
	v_subrev_u32_e32 v206, 50, v0
	v_fmac_f32_e32 v205, 0x3e38aa3b, v216
	v_cndmask_b32_e32 v204, v179, v204, vcc
	v_cmp_gt_u32_e32 vcc, s70, v206
	v_add_f32_e32 v202, v188, v202
	s_and_b64 vcc, s[0:1], vcc
	v_subrev_u32_e32 v0, 51, v0
	v_fmac_f32_e32 v202, 0x3e38aa3b, v217
	v_cndmask_b32_e32 v205, v179, v205, vcc
	v_cmp_gt_u32_e32 vcc, s70, v0
	s_and_b64 vcc, s[0:1], vcc
	v_exp_f32_e32 v228, v203
	v_cndmask_b32_e32 v0, v179, v202, vcc
	v_exp_f32_e32 v229, v204
	v_exp_f32_e32 v230, v205
	ds_read_b128 v[202:205], v193 offset:40960
	ds_read_b128 v[206:209], v193 offset:43520
	ds_read_b128 v[210:213], v193 offset:46080
	ds_read_b128 v[214:217], v193 offset:48640
	v_exp_f32_e32 v14, v14
	v_exp_f32_e32 v15, v15
	v_exp_f32_e32 v1, v1
	v_exp_f32_e32 v231, v0
	s_nop 0
	v_cvt_pk_bf16_f32 v218, v14, v15
	v_cvt_pk_bf16_f32 v219, v219, v1
	v_cvt_pk_bf16_f32 v220, v220, v221
	v_cvt_pk_bf16_f32 v221, v222, v223
	s_setprio 1
	s_waitcnt lgkmcnt(3)
	v_mfma_f32_16x16x32_bf16 v[0:3], v[202:205], v[218:221], v[2:5]
	s_waitcnt lgkmcnt(2)
	v_mfma_f32_16x16x32_bf16 v[4:7], v[206:209], v[218:221], v[6:9]
	s_waitcnt lgkmcnt(1)
	v_mfma_f32_16x16x32_bf16 v[8:11], v[210:213], v[218:221], v[10:13]
	s_waitcnt lgkmcnt(0)
	v_mfma_f32_16x16x32_bf16 v[12:15], v[214:217], v[218:221], v[198:201]
	v_mfma_f32_16x16x32_bf16 v[194:197], v[80:83], v[218:221], v[194:197]
	s_setprio 0
	s_nop 0
	ds_read_b128 v[198:201], v193 offset:41024
	ds_read_b128 v[202:205], v193 offset:43584
	ds_read_b128 v[206:209], v193 offset:46144
	ds_read_b128 v[210:213], v193 offset:48704
	v_cvt_pk_bf16_f32 v214, v224, v225
	v_cvt_pk_bf16_f32 v215, v226, v227
	v_cvt_pk_bf16_f32 v216, v228, v229
	v_cvt_pk_bf16_f32 v217, v230, v231
	s_setprio 1
	s_waitcnt lgkmcnt(3)
	v_mfma_f32_16x16x32_bf16 v[0:3], v[198:201], v[214:217], v[0:3]
	s_mov_b64 s[22:23], 0
	s_waitcnt lgkmcnt(2)
	v_mfma_f32_16x16x32_bf16 v[4:7], v[202:205], v[214:217], v[4:7]
	s_waitcnt lgkmcnt(1)
	v_mfma_f32_16x16x32_bf16 v[8:11], v[206:209], v[214:217], v[8:11]
	s_waitcnt lgkmcnt(0)
	v_mfma_f32_16x16x32_bf16 v[12:15], v[210:213], v[214:217], v[12:15]
	v_mfma_f32_16x16x32_bf16 v[80:83], v[80:83], v[214:217], v[194:197]
.LBB0_1046:
	s_andn2_b64 vcc, exec, s[22:23]
	s_cbranch_vccnz .LBB0_1048
	s_mov_b32 s101, 0
	s_mov_b32 s29, s28
	s_sub_i32 s22, s81, 64
	s_and_b32 s22, s22, 0xc0
	s_mulk_i32 s22, 0xa0
	v_add_u32_e32 v193, s22, v153
	v_pk_mov_b32 v[80:81], s[28:29], s[28:29] op_sel:[0,1]
	v_pk_mov_b32 v[82:83], s[28:29], s[28:29] op_sel:[0,1]
	s_waitcnt lgkmcnt(7)
	v_mfma_f32_16x16x32_bf16 v[0:3], v[88:91], v[60:63], 0
	s_waitcnt lgkmcnt(5)
	v_mfma_f32_16x16x32_bf16 v[4:7], v[96:99], v[60:63], 0
	s_waitcnt lgkmcnt(3)
	v_mfma_f32_16x16x32_bf16 v[8:11], v[104:107], v[60:63], 0
	s_waitcnt lgkmcnt(1)
	v_mfma_f32_16x16x32_bf16 v[12:15], v[112:115], v[60:63], 0
	v_mfma_f32_16x16x32_bf16 v[0:3], v[92:95], v[56:59], v[0:3]
	v_mfma_f32_16x16x32_bf16 v[4:7], v[100:103], v[56:59], v[4:7]
	v_mfma_f32_16x16x32_bf16 v[8:11], v[108:111], v[56:59], v[8:11]
	s_waitcnt lgkmcnt(0)
	v_mfma_f32_16x16x32_bf16 v[12:15], v[116:119], v[56:59], v[12:15]
	s_setprio 0
	ds_read_b128 v[88:91], v143 offset:40960
	ds_read_b128 v[92:95], v143 offset:43520
	ds_read_b128 v[96:99], v143 offset:46080
	ds_read_b128 v[100:103], v143 offset:48640
	ds_read_b128 v[104:107], v143 offset:41024
	ds_read_b128 v[108:111], v143 offset:43584
	ds_read_b128 v[112:115], v143 offset:46144
	ds_read_b128 v[116:119], v143 offset:48704
	ds_read_b128 v[194:197], v193
	ds_read_b128 v[198:201], v193 offset:64
	ds_read_b128 v[202:205], v193 offset:2560
	ds_read_b128 v[206:209], v193 offset:2624
	ds_read_b128 v[210:213], v193 offset:5120
	ds_read_b128 v[214:217], v193 offset:5184
	ds_read_b128 v[218:221], v193 offset:7680
	v_mul_f32_e64 v226, -v146, v147
	v_cndmask_b32_e64 v226, v179, v226, s[20:21]
	v_add_f32_e32 v227, v192, v226
	v_add_f32_e32 v228, v146, v227
	v_add_f32_e32 v229, v137, v227
	v_add_f32_e32 v230, v188, v227
	v_fmamk_f32 v0, v0, 0x3e38aa3b, v227
	v_fmamk_f32 v1, v1, 0x3e38aa3b, v228
	v_fmamk_f32 v2, v2, 0x3e38aa3b, v229
	v_fmamk_f32 v3, v3, 0x3e38aa3b, v230
	v_exp_f32_e32 v0, v0
	v_exp_f32_e32 v1, v1
	v_exp_f32_e32 v2, v2
	v_exp_f32_e32 v3, v3
	v_add_f32_e32 v227, v189, v226
	v_add_f32_e32 v228, v146, v227
	v_add_f32_e32 v229, v137, v227
	v_add_f32_e32 v230, v188, v227
	v_fmamk_f32 v4, v4, 0x3e38aa3b, v227
	v_fmamk_f32 v5, v5, 0x3e38aa3b, v228
	v_fmamk_f32 v6, v6, 0x3e38aa3b, v229
	v_fmamk_f32 v7, v7, 0x3e38aa3b, v230
	v_exp_f32_e32 v4, v4
	v_exp_f32_e32 v5, v5
	v_exp_f32_e32 v6, v6
	v_exp_f32_e32 v7, v7
	v_add_f32_e32 v227, v190, v226
	v_add_f32_e32 v228, v146, v227
	v_add_f32_e32 v229, v137, v227
	v_add_f32_e32 v230, v188, v227
	v_fmamk_f32 v8, v8, 0x3e38aa3b, v227
	v_fmamk_f32 v9, v9, 0x3e38aa3b, v228
	v_fmamk_f32 v10, v10, 0x3e38aa3b, v229
	v_fmamk_f32 v11, v11, 0x3e38aa3b, v230
	v_exp_f32_e32 v8, v8
	v_exp_f32_e32 v9, v9
	v_exp_f32_e32 v10, v10
	v_exp_f32_e32 v11, v11
	v_add_f32_e32 v227, v191, v226
	v_add_f32_e32 v228, v146, v227
	v_add_f32_e32 v229, v137, v227
	v_add_f32_e32 v230, v188, v227
	v_fmamk_f32 v12, v12, 0x3e38aa3b, v227
	v_fmamk_f32 v13, v13, 0x3e38aa3b, v228
	v_fmamk_f32 v14, v14, 0x3e38aa3b, v229
	v_fmamk_f32 v15, v15, 0x3e38aa3b, v230
	v_exp_f32_e32 v12, v12
	v_exp_f32_e32 v13, v13
	v_exp_f32_e32 v14, v14
	v_exp_f32_e32 v15, v15
	v_cvt_pk_bf16_f32 v226, v0, v1
	v_cvt_pk_bf16_f32 v227, v2, v3
	v_cvt_pk_bf16_f32 v228, v4, v5
	v_cvt_pk_bf16_f32 v229, v6, v7
	v_cvt_pk_bf16_f32 v230, v8, v9
	v_cvt_pk_bf16_f32 v231, v10, v11
	v_cvt_pk_bf16_f32 v232, v12, v13
	v_cvt_pk_bf16_f32 v233, v14, v15
	s_nop 1
	s_setprio 1
	s_waitcnt lgkmcnt(14)
	v_mfma_f32_16x16x32_bf16 v[36:39], v[88:91], v[226:229], v[36:39]
	ds_read_b128 v[222:225], v193 offset:7744
	s_waitcnt lgkmcnt(14)
	v_mfma_f32_16x16x32_bf16 v[40:43], v[92:95], v[226:229], v[40:43]
	s_waitcnt lgkmcnt(13)
	v_mfma_f32_16x16x32_bf16 v[44:47], v[96:99], v[226:229], v[44:47]
	s_waitcnt lgkmcnt(12)
	v_mfma_f32_16x16x32_bf16 v[84:87], v[100:103], v[226:229], v[84:87]
	v_mfma_f32_16x16x32_bf16 v[32:35], v[80:83], v[226:229], v[32:35]
	s_waitcnt lgkmcnt(11)
	v_mfma_f32_16x16x32_bf16 v[36:39], v[104:107], v[230:233], v[36:39]
	s_waitcnt lgkmcnt(10)
	v_mfma_f32_16x16x32_bf16 v[40:43], v[108:111], v[230:233], v[40:43]
	s_waitcnt lgkmcnt(9)
	v_mfma_f32_16x16x32_bf16 v[44:47], v[112:115], v[230:233], v[44:47]
	s_waitcnt lgkmcnt(8)
	v_mfma_f32_16x16x32_bf16 v[84:87], v[116:119], v[230:233], v[84:87]
	v_mfma_f32_16x16x32_bf16 v[32:35], v[80:83], v[230:233], v[32:35]
	s_waitcnt lgkmcnt(7)
	v_mfma_f32_16x16x32_bf16 v[0:3], v[194:197], v[60:63], 0
	s_waitcnt lgkmcnt(5)
	v_mfma_f32_16x16x32_bf16 v[4:7], v[202:205], v[60:63], 0
	s_waitcnt lgkmcnt(3)
	v_mfma_f32_16x16x32_bf16 v[8:11], v[210:213], v[60:63], 0
	s_waitcnt lgkmcnt(1)
	v_mfma_f32_16x16x32_bf16 v[12:15], v[218:221], v[60:63], 0
	v_mfma_f32_16x16x32_bf16 v[0:3], v[198:201], v[56:59], v[0:3]
	v_mfma_f32_16x16x32_bf16 v[4:7], v[206:209], v[56:59], v[4:7]
	v_mfma_f32_16x16x32_bf16 v[8:11], v[214:217], v[56:59], v[8:11]
	s_waitcnt lgkmcnt(0)
	v_mfma_f32_16x16x32_bf16 v[12:15], v[222:225], v[56:59], v[12:15]
	s_setprio 0
	ds_read_b128 v[194:197], v193 offset:40960
	ds_read_b128 v[198:201], v193 offset:43520
	ds_read_b128 v[202:205], v193 offset:46080
	ds_read_b128 v[206:209], v193 offset:48640
	ds_read_b128 v[210:213], v193 offset:41024
	ds_read_b128 v[214:217], v193 offset:43584
	ds_read_b128 v[218:221], v193 offset:46144
	ds_read_b128 v[222:225], v193 offset:48704
	v_mul_f32_e64 v226, -v146, v141
	v_cndmask_b32_e64 v226, v179, v226, s[0:1]
	v_add_f32_e32 v227, v192, v226
	v_add_f32_e32 v228, v146, v227
	v_add_f32_e32 v229, v137, v227
	v_add_f32_e32 v230, v188, v227
	v_fmamk_f32 v0, v0, 0x3e38aa3b, v227
	v_fmamk_f32 v1, v1, 0x3e38aa3b, v228
	v_fmamk_f32 v2, v2, 0x3e38aa3b, v229
	v_fmamk_f32 v3, v3, 0x3e38aa3b, v230
	v_exp_f32_e32 v0, v0
	v_exp_f32_e32 v1, v1
	v_exp_f32_e32 v2, v2
	v_exp_f32_e32 v3, v3
	v_add_f32_e32 v227, v189, v226
	v_add_f32_e32 v228, v146, v227
	v_add_f32_e32 v229, v137, v227
	v_add_f32_e32 v230, v188, v227
	v_fmamk_f32 v4, v4, 0x3e38aa3b, v227
	v_fmamk_f32 v5, v5, 0x3e38aa3b, v228
	v_fmamk_f32 v6, v6, 0x3e38aa3b, v229
	v_fmamk_f32 v7, v7, 0x3e38aa3b, v230
	v_exp_f32_e32 v4, v4
	v_exp_f32_e32 v5, v5
	v_exp_f32_e32 v6, v6
	v_exp_f32_e32 v7, v7
	v_add_f32_e32 v227, v190, v226
	v_add_f32_e32 v228, v146, v227
	v_add_f32_e32 v229, v137, v227
	v_add_f32_e32 v230, v188, v227
	v_fmamk_f32 v8, v8, 0x3e38aa3b, v227
	v_fmamk_f32 v9, v9, 0x3e38aa3b, v228
	v_fmamk_f32 v10, v10, 0x3e38aa3b, v229
	v_fmamk_f32 v11, v11, 0x3e38aa3b, v230
	v_exp_f32_e32 v8, v8
	v_exp_f32_e32 v9, v9
	v_exp_f32_e32 v10, v10
	v_exp_f32_e32 v11, v11
	v_add_f32_e32 v227, v191, v226
	v_add_f32_e32 v228, v146, v227
	v_add_f32_e32 v229, v137, v227
	v_add_f32_e32 v230, v188, v227
	v_fmamk_f32 v12, v12, 0x3e38aa3b, v227
	v_fmamk_f32 v13, v13, 0x3e38aa3b, v228
	v_fmamk_f32 v14, v14, 0x3e38aa3b, v229
	v_fmamk_f32 v15, v15, 0x3e38aa3b, v230
	v_exp_f32_e32 v12, v12
	v_exp_f32_e32 v13, v13
	v_exp_f32_e32 v14, v14
	v_exp_f32_e32 v15, v15
	v_cvt_pk_bf16_f32 v226, v0, v1
	v_cvt_pk_bf16_f32 v227, v2, v3
	v_cvt_pk_bf16_f32 v228, v4, v5
	v_cvt_pk_bf16_f32 v229, v6, v7
	v_cvt_pk_bf16_f32 v230, v8, v9
	v_cvt_pk_bf16_f32 v231, v10, v11
	v_cvt_pk_bf16_f32 v232, v12, v13
	v_cvt_pk_bf16_f32 v233, v14, v15
	s_nop 1
	s_setprio 1
	s_waitcnt lgkmcnt(7)
	v_mfma_f32_16x16x32_bf16 v[36:39], v[194:197], v[226:229], v[36:39]
	s_waitcnt lgkmcnt(6)
	v_mfma_f32_16x16x32_bf16 v[40:43], v[198:201], v[226:229], v[40:43]
	s_waitcnt lgkmcnt(5)
	v_mfma_f32_16x16x32_bf16 v[44:47], v[202:205], v[226:229], v[44:47]
	s_waitcnt lgkmcnt(4)
	v_mfma_f32_16x16x32_bf16 v[84:87], v[206:209], v[226:229], v[84:87]
	v_mfma_f32_16x16x32_bf16 v[32:35], v[80:83], v[226:229], v[32:35]
	s_waitcnt lgkmcnt(3)
	v_mfma_f32_16x16x32_bf16 v[36:39], v[210:213], v[230:233], v[36:39]
	s_waitcnt lgkmcnt(2)
	v_mfma_f32_16x16x32_bf16 v[40:43], v[214:217], v[230:233], v[40:43]
	s_waitcnt lgkmcnt(1)
	v_mfma_f32_16x16x32_bf16 v[44:47], v[218:221], v[230:233], v[44:47]
	s_waitcnt lgkmcnt(0)
	v_mfma_f32_16x16x32_bf16 v[84:87], v[222:225], v[230:233], v[84:87]
	v_mfma_f32_16x16x32_bf16 v[32:35], v[80:83], v[230:233], v[32:35]
.LBB0_1048:
	s_setprio 0
	s_sub_i32 s0, s80, s83
	s_add_i32 s1, s0, 1
	s_max_i32 s1, s1, 0
	s_max_i32 s0, s0, 0
	s_lshl_b32 s1, s1, 2
	s_add_i32 s1, s1, 0x24900
	v_mov_b32_e32 v194, s1
	ds_read_b32 v194, v194
	s_lshl_b32 s0, s0, 2
	s_add_i32 s0, s0, 0x24900
	v_mov_b32_e32 v195, s0
	ds_read_b32 v195, v195
	s_and_b32 s0, s81, 0x80
	s_mulk_i32 s0, 0xa0
	v_add_u32_e32 v193, s0, v151
	s_waitcnt vmcnt(3)
	ds_write_b128 v193, v[20:23]
	v_add_u32_e32 v20, s0, v152
	s_add_i32 s0, s81, 64
	s_and_b32 s0, s0, 0xc0
	v_add_u32_e32 v20, 0xa000, v20
	s_mulk_i32 s0, 0xa0
	s_waitcnt vmcnt(2)
	ds_write2_b64 v20, v[16:17], v[18:19] offset1:2
	v_add_u32_e32 v16, s0, v151
	s_waitcnt vmcnt(1)
	ds_write_b128 v16, v[28:31]
	v_add_u32_e32 v16, s0, v152
	s_add_i32 s0, s83, -1
	s_cmp_lt_u32 s0, s79
	s_cselect_b32 s0, s0, s80
	s_lshl_b32 s0, s0, 2
	s_add_i32 s22, 0, 0x24900
	v_add_u32_e32 v16, 0xa000, v16
	s_add_i32 s0, s22, s0
	s_waitcnt vmcnt(0)
	ds_write2_b64 v16, v[24:25], v[26:27] offset1:2
	s_waitcnt lgkmcnt(4)
	v_readfirstlane_b32 s98, v194
	v_readfirstlane_b32 s99, v195
	s_addk_i32 s81, 0x80
	s_add_i32 s82, s82, 8
	s_add_i32 s1, s83, -1
	s_cmp_ge_u32 s1, s79
	s_cbranch_scc1 .Lsel_skip_pf
	s_lshl_b32 s0, s98, 6
	s_ashr_i32 s1, s0, 31
	s_lshl_b64 s[20:21], s[0:1], 12
	v_lshl_add_u64 v[18:19], s[0:1], 1, v[148:149]
	v_lshl_add_u64 v[16:17], v[120:121], 0, s[20:21]
	global_load_dwordx4 v[20:23], v[16:17], off offset:2560
	s_nop 0
	global_load_dwordx4 v[16:19], v[18:19], off
	s_lshl_b32 s0, s99, 6
	s_ashr_i32 s1, s0, 31
	s_lshl_b64 s[20:21], s[0:1], 12
	v_lshl_add_u64 v[24:25], v[120:121], 0, s[20:21]
	v_lshl_add_u64 v[26:27], s[0:1], 1, v[148:149]
	global_load_dwordx4 v[28:31], v[24:25], off offset:2560
	s_nop 0
	global_load_dwordx4 v[24:27], v[26:27], off
.Lsel_skip_pf:
	s_waitcnt lgkmcnt(0)
	s_barrier
	s_mov_b32 s32, s89
	s_mov_b32 s97, s91
	s_mov_b32 s89, s98
	s_mov_b32 s91, s99
	s_add_i32 s0, s83, 2
	s_add_i32 s1, s83, -2
	s_cmp_lt_u32 s1, s79
	s_cbranch_scc0 .LBB0_1051
	s_mov_b32 s83, s0
	s_cmp_eq_u32 s101, 0
	s_cbranch_scc1 .LBB0_1040
	v_pk_mov_b32 v[32:33], v[80:81], v[80:81] op_sel:[0,1]
	v_pk_mov_b32 v[34:35], v[82:83], v[82:83] op_sel:[0,1]
	v_pk_mov_b32 v[36:37], v[0:1], v[0:1] op_sel:[0,1]
	v_pk_mov_b32 v[38:39], v[2:3], v[2:3] op_sel:[0,1]
	v_pk_mov_b32 v[40:41], v[4:5], v[4:5] op_sel:[0,1]
	v_pk_mov_b32 v[42:43], v[6:7], v[6:7] op_sel:[0,1]
	v_pk_mov_b32 v[44:45], v[8:9], v[8:9] op_sel:[0,1]
	v_pk_mov_b32 v[46:47], v[10:11], v[10:11] op_sel:[0,1]
	v_pk_mov_b32 v[84:85], v[12:13], v[12:13] op_sel:[0,1]
	v_pk_mov_b32 v[86:87], v[14:15], v[14:15] op_sel:[0,1]
	s_branch .LBB0_1040

.LBB0_1051:
	s_cmp_eq_u32 s101, 0
	s_cbranch_scc0 .Lsel_exit_ok
	v_pk_mov_b32 v[0:1], v[36:37], v[36:37] op_sel:[0,1]
	v_pk_mov_b32 v[2:3], v[38:39], v[38:39] op_sel:[0,1]
	v_pk_mov_b32 v[4:5], v[40:41], v[40:41] op_sel:[0,1]
	v_pk_mov_b32 v[6:7], v[42:43], v[42:43] op_sel:[0,1]
	v_pk_mov_b32 v[8:9], v[44:45], v[44:45] op_sel:[0,1]
	v_pk_mov_b32 v[10:11], v[46:47], v[46:47] op_sel:[0,1]
	v_pk_mov_b32 v[12:13], v[84:85], v[84:85] op_sel:[0,1]
	v_pk_mov_b32 v[14:15], v[86:87], v[86:87] op_sel:[0,1]
	v_pk_mov_b32 v[80:81], v[32:33], v[32:33] op_sel:[0,1]
	v_pk_mov_b32 v[82:83], v[34:35], v[34:35] op_sel:[0,1]
